# seam 6 (up->down) as a 4-workgroup panel barrier plus late global guard; decode rows handed over write-through
# speedup vs baseline: 1.0121x; 1.0031x over previous
.LBB0_2:
	s_or_b64 exec, exec, s[4:5]
	s_load_dwordx8 s[8:15], s[0:1], 0x80
	s_waitcnt lgkmcnt(0)
	s_barrier
	s_add_u32 s2, s14, 0x1000
	s_addc_u32 s3, s15, 0
	v_writelane_b32 v252, s2, 11
	s_nop 1
	v_writelane_b32 v252, s3, 12
	s_getreg_b32 s2, hwreg(HW_REG_XCC_ID, 0, 4)
	s_and_b32 s2, s2, 15
	v_writelane_b32 v252, s2, 13
	s_mov_b64 s[4:5], exec
	v_readlane_b32 s2, v252, 9
	v_readlane_b32 s3, v252, 10
	s_and_b64 s[2:3], s[4:5], s[2:3]
	s_mov_b64 exec, s[2:3]
	s_cbranch_execz .LBB0_5
	s_mov_b64 s[8:9], exec
	v_mbcnt_lo_u32_b32 v1, s8, 0
	v_mbcnt_hi_u32_b32 v1, s9, v1
	v_cmp_eq_u32_e32 vcc, 0, v1
	s_and_b64 s[2:3], exec, vcc
	s_mov_b64 exec, s[2:3]
	s_cbranch_execz .LBB0_5
	v_readlane_b32 s2, v252, 13
	s_lshl_b32 s2, s2, 8
	s_bcnt1_i32_b64 s3, s[8:9]
	v_mov_b32_e32 v1, s2
	v_mov_b32_e32 v2, s3
	v_readlane_b32 s2, v252, 11
	v_readlane_b32 s3, v252, 12
	s_nop 4
	global_atomic_add v1, v2, s[2:3] offset:1024
	v_readlane_b32 s8, v252, 13
	s_add_i32 s8, s8, 1
	v_mov_b32_e32 v4, s8
	s_lshl_b32 s8, s54, 2
	s_addk_i32 s8, 0x3800
	v_mov_b32_e32 v3, s8
	global_store_dword v3, v4, s[2:3] sc0 sc1

.LBB0_307:
	s_waitcnt vmcnt(0)
	s_barrier
	s_mov_b64 s[0:1], exec
	v_readlane_b32 s2, v252, 9
	v_readlane_b32 s3, v252, 10
	s_and_b64 s[2:3], s[0:1], s[2:3]
	s_mov_b64 exec, s[2:3]
	s_cbranch_execz .LBB0_359
	v_readlane_b32 s30, v252, 11
	v_readlane_b32 s31, v252, 12
	v_readlane_b32 s32, v252, 13
	v_mov_b32_e32 v5, 1
	v_mov_b32_e32 v22, 0
	s_add_u32 s34, s30, 0x1400
	s_addc_u32 s35, s31, 0
	s_lshl_b32 s32, s32, 8
	s_add_u32 s40, s30, 0x3400
	s_addc_u32 s41, s31, 0
	v_mov_b32_e32 v4, s32
	s_mov_b32 s42, 0
	s_and_b32 s36, s54, 63
	s_lshl_b32 s36, s36, 2
	s_addk_i32 s36, 0x3800
	v_mov_b32_e32 v9, s36
	global_load_dword v10, v9, s[30:31] sc1
	global_load_dword v11, v9, s[30:31] offset:256 sc1
	global_load_dword v12, v9, s[30:31] offset:512 sc1
	global_load_dword v13, v9, s[30:31] offset:768 sc1
	global_atomic_add v6, v4, v5, s[34:35] sc0
	s_mul_i32 s33, s86, 2
	s_mul_i32 s39, s98, 2
	s_waitcnt vmcnt(0)
	v_readfirstlane_b32 s38, v6
	v_readfirstlane_b32 s36, v10
	v_readfirstlane_b32 s37, v11
	v_readfirstlane_b32 s43, v12
	v_readfirstlane_b32 s44, v13
	s_cmp_lg_u32 s36, s37
	s_cselect_b32 s99, 1, 0
	s_cmp_lg_u32 s36, s43
	s_cselect_b32 s37, 1, 0
	s_or_b32 s99, s99, s37
	s_cmp_lg_u32 s36, s44
	s_cselect_b32 s37, 1, 0
	s_or_b32 s99, s99, s37
	s_cmp_eq_u32 s36, 0
	s_cselect_b32 s37, 1, 0
	s_or_b32 s99, s99, s37
	v_mov_b32_e32 v7, s98
	s_add_i32 s38, s38, 1
	s_cmp_lg_u32 s38, s39
	s_cbranch_scc1 .Lxb2_spin
	buffer_wbl2 sc1
	s_waitcnt vmcnt(0)
	global_atomic_add v22, v7, s[40:41]

.LBB0_1089:
	s_and_b32 s38, s29, 0xffffffe0
	s_ashr_i32 s39, s38, 31
	s_lshl_b64 s[38:39], s[38:39], 11
	s_add_u32 s38, s20, s38
	s_addc_u32 s39, s21, s39
	s_and_b32 s37, s24, 0x10000
	s_lshl_b32 s37, s37, 1
	s_add_u32 s40, s8, s37
	s_addc_u32 s41, s9, 0
	v_lshl_add_u64 v[96:97], s[38:39], 0, v[2:3]
	v_lshl_add_u64 v[68:69], s[40:41], 0, v[4:5]
	global_load_dwordx4 v[12:15], v[96:97], off
	v_add_co_u32_e32 v16, vcc, s31, v68
	v_lshl_add_u64 v[98:99], s[38:39], 0, v[0:1]
	s_nop 0
	v_addc_co_u32_e32 v17, vcc, 0, v69, vcc
	v_add_co_u32_e32 v40, vcc, s33, v68
	global_load_dwordx4 v[16:19], v[16:17], off
	s_nop 0
	v_addc_co_u32_e32 v41, vcc, 0, v69, vcc
	v_add_co_u32_e32 v52, vcc, s34, v68
	global_load_dwordx4 v[20:23], v[98:99], off
	global_load_dwordx4 v[24:27], v[96:97], off offset:64
	global_load_dwordx4 v[28:31], v[98:99], off offset:64
	v_addc_co_u32_e32 v53, vcc, 0, v69, vcc
	v_add_co_u32_e32 v64, vcc, s35, v68
	v_lshl_add_u64 v[76:77], v[68:69], 0, s[6:7]
	v_lshl_add_u64 v[80:81], v[68:69], 0, s[10:11]
	v_lshl_add_u64 v[88:89], v[68:69], 0, s[12:13]
	v_addc_co_u32_e32 v65, vcc, 0, v69, vcc
	v_lshl_add_u64 v[100:101], v[68:69], 0, s[14:15]
	global_load_dwordx4 v[32:35], v[76:77], off offset:192
	global_load_dwordx4 v[44:47], v[80:81], off offset:192
	global_load_dwordx4 v[56:59], v[88:89], off offset:192
	global_load_dwordx4 v[68:71], v[100:101], off offset:192
	s_add_i32 s37, s2, s36
	global_load_dwordx4 v[40:43], v[40:41], off
	s_cmpk_gt_i32 s37, 0x3ff
	global_load_dwordx4 v[52:55], v[52:53], off
	s_cselect_b64 s[38:39], -1, 0
	global_load_dwordx4 v[64:67], v[64:65], off
	s_nop 0
	global_load_dwordx4 v[72:75], v[76:77], off offset:64
	s_nop 0
	global_load_dwordx4 v[76:79], v[76:77], off offset:128
	s_or_b64 s[38:39], s[16:17], s[38:39]
	s_and_b64 vcc, exec, s[38:39]
	s_waitcnt vmcnt(12)
	v_mfma_f32_16x16x32_bf16 v[36:39], v[12:15], v[16:19], 0
	s_waitcnt vmcnt(11)
	v_mfma_f32_16x16x32_bf16 v[16:19], v[20:23], v[16:19], 0
	s_waitcnt vmcnt(1)
	v_mfma_f32_16x16x32_bf16 v[36:39], v[24:27], v[72:75], v[36:39]
	v_mfma_f32_16x16x32_bf16 v[16:19], v[28:31], v[72:75], v[16:19]
	global_load_dwordx4 v[72:75], v[80:81], off offset:64
	s_nop 0
	global_load_dwordx4 v[80:83], v[80:81], off offset:128
	s_nop 0
	global_load_dwordx4 v[84:87], v[88:89], off offset:64
	v_mfma_f32_16x16x32_bf16 v[48:51], v[12:15], v[40:43], 0
	v_mfma_f32_16x16x32_bf16 v[40:43], v[20:23], v[40:43], 0
	v_mfma_f32_16x16x32_bf16 v[60:63], v[12:15], v[52:55], 0
	v_mfma_f32_16x16x32_bf16 v[52:55], v[20:23], v[52:55], 0
	v_mfma_f32_16x16x32_bf16 v[12:15], v[12:15], v[64:67], 0
	v_mfma_f32_16x16x32_bf16 v[20:23], v[20:23], v[64:67], 0
	s_waitcnt vmcnt(2)
	v_mfma_f32_16x16x32_bf16 v[48:51], v[24:27], v[72:75], v[48:51]
	v_mfma_f32_16x16x32_bf16 v[40:43], v[28:31], v[72:75], v[40:43]
	global_load_dwordx4 v[72:75], v[96:97], off offset:128
	s_nop 0
	global_load_dwordx4 v[88:91], v[88:89], off offset:128
	s_nop 0
	global_load_dwordx4 v[92:95], v[98:99], off offset:128
	s_waitcnt vmcnt(3)
	v_mfma_f32_16x16x32_bf16 v[60:63], v[24:27], v[84:87], v[60:63]
	v_mfma_f32_16x16x32_bf16 v[52:55], v[28:31], v[84:87], v[52:55]
	global_load_dwordx4 v[84:87], v[96:97], off offset:192
	s_nop 0
	global_load_dwordx4 v[96:99], v[98:99], off offset:192
	s_waitcnt vmcnt(4)
	v_mfma_f32_16x16x32_bf16 v[36:39], v[72:75], v[76:79], v[36:39]
	s_waitcnt vmcnt(2)
	v_mfma_f32_16x16x32_bf16 v[16:19], v[92:95], v[76:79], v[16:19]
	v_mfma_f32_16x16x32_bf16 v[48:51], v[72:75], v[80:83], v[48:51]
	v_mfma_f32_16x16x32_bf16 v[52:55], v[92:95], v[88:91], v[52:55]
	v_mfma_f32_16x16x32_bf16 v[40:43], v[92:95], v[80:83], v[40:43]
	v_mfma_f32_16x16x32_bf16 v[60:63], v[72:75], v[88:91], v[60:63]
	s_waitcnt vmcnt(1)
	v_mfma_f32_16x16x32_bf16 v[36:39], v[84:87], v[32:35], v[36:39]
	s_waitcnt vmcnt(0)
	v_mfma_f32_16x16x32_bf16 v[16:19], v[96:99], v[32:35], v[16:19]
	v_mfma_f32_16x16x32_bf16 v[32:35], v[84:87], v[44:47], v[48:51]
	s_nop 4
	ds_write_b128 v11, v[36:39]
	v_mfma_f32_16x16x32_bf16 v[48:51], v[96:99], v[56:59], v[52:55]
	s_nop 2
	global_load_dwordx4 v[52:55], v[100:101], off offset:64
	v_mfma_f32_16x16x32_bf16 v[40:43], v[96:99], v[44:47], v[40:43]
	v_mfma_f32_16x16x32_bf16 v[44:47], v[84:87], v[56:59], v[60:63]
	global_load_dwordx4 v[56:59], v[100:101], off offset:128
	ds_write_b128 v11, v[16:19] offset:1024
	ds_write_b128 v11, v[32:35] offset:16384
	s_nop 3
	ds_write_b128 v11, v[40:43] offset:17408
	s_waitcnt vmcnt(1)
	v_mfma_f32_16x16x32_bf16 v[12:15], v[24:27], v[52:55], v[12:15]
	v_mfma_f32_16x16x32_bf16 v[20:23], v[28:31], v[52:55], v[20:23]
	s_waitcnt vmcnt(0)
	v_mfma_f32_16x16x32_bf16 v[12:15], v[72:75], v[56:59], v[12:15]
	v_mfma_f32_16x16x32_bf16 v[20:23], v[92:95], v[56:59], v[20:23]
	v_mfma_f32_16x16x32_bf16 v[12:15], v[84:87], v[68:71], v[12:15]
	ds_write_b128 v11, v[44:47] offset:32768
	ds_write_b128 v11, v[48:51] offset:33792
	s_nop 5
	ds_write_b128 v11, v[12:15] offset:49152
	v_mfma_f32_16x16x32_bf16 v[12:15], v[96:99], v[68:71], v[20:23]
	s_nop 7
	ds_write_b128 v11, v[12:15] offset:50176
	s_waitcnt lgkmcnt(0)
	s_barrier
	s_cbranch_vccnz .LBB0_1088
	s_and_b32 s37, s26, 0x70
	v_or_b32_e32 v6, s37, v8
	v_lshlrev_b32_e32 v12, 2, v6
	global_load_dword v76, v12, s[0:1]
	v_add_u32_e32 v72, s22, v10
	ds_read_b128 v[12:15], v72
	ds_read_b128 v[16:19], v72 offset:1024
	ds_read_b128 v[20:23], v72 offset:2048
	ds_read_b128 v[24:27], v72 offset:3072
	ds_read_b128 v[28:31], v72 offset:4096
	ds_read_b128 v[32:35], v72 offset:5120
	ds_read_b128 v[36:39], v72 offset:6144
	ds_read_b128 v[40:43], v72 offset:7168
	ds_read_b128 v[44:47], v72 offset:8192
	ds_read_b128 v[48:51], v72 offset:9216
	ds_read_b128 v[52:55], v72 offset:10240
	ds_read_b128 v[56:59], v72 offset:11264
	ds_read_b128 v[60:63], v72 offset:12288
	ds_read_b128 v[64:67], v72 offset:13312
	ds_read_b128 v[68:71], v72 offset:14336
	ds_read_b128 v[72:75], v72 offset:15360
	s_waitcnt lgkmcnt(13)
	v_pk_add_f32 v[14:15], v[14:15], v[22:23]
	v_pk_add_f32 v[12:13], v[12:13], v[20:21]
	s_waitcnt lgkmcnt(12)
	v_pk_add_f32 v[16:17], v[16:17], v[24:25]
	v_pk_add_f32 v[18:19], v[18:19], v[26:27]
	s_waitcnt lgkmcnt(11)
	v_pk_add_f32 v[14:15], v[14:15], v[30:31]
	v_pk_add_f32 v[12:13], v[12:13], v[28:29]
	s_waitcnt lgkmcnt(10)
	v_pk_add_f32 v[16:17], v[16:17], v[32:33]
	v_pk_add_f32 v[18:19], v[18:19], v[34:35]
	s_waitcnt lgkmcnt(9)
	v_pk_add_f32 v[14:15], v[14:15], v[38:39]
	v_pk_add_f32 v[12:13], v[12:13], v[36:37]
	s_waitcnt lgkmcnt(8)
	v_pk_add_f32 v[16:17], v[16:17], v[40:41]
	s_add_i32 s37, s28, s29
	v_pk_add_f32 v[18:19], v[18:19], v[42:43]
	s_waitcnt lgkmcnt(7)
	v_pk_add_f32 v[14:15], v[14:15], v[46:47]
	v_pk_add_f32 v[12:13], v[12:13], v[44:45]
	s_waitcnt lgkmcnt(6)
	v_pk_add_f32 v[16:17], v[16:17], v[48:49]
	s_andn2_b32 s37, s37, 31
	v_readlane_b32 s40, v252, 0
	v_pk_add_f32 v[18:19], v[18:19], v[50:51]
	s_waitcnt lgkmcnt(5)
	v_pk_add_f32 v[14:15], v[14:15], v[54:55]
	v_pk_add_f32 v[12:13], v[12:13], v[52:53]
	s_waitcnt lgkmcnt(4)
	v_pk_add_f32 v[16:17], v[16:17], v[56:57]
	v_or_b32_e32 v78, s37, v9
	v_lshlrev_b32_e32 v6, 13, v6
	v_readlane_b32 s46, v252, 6
	v_readlane_b32 s47, v252, 7
	v_pk_add_f32 v[18:19], v[18:19], v[58:59]
	s_waitcnt lgkmcnt(3)
	v_pk_add_f32 v[14:15], v[14:15], v[62:63]
	v_pk_add_f32 v[12:13], v[12:13], v[60:61]
	s_waitcnt lgkmcnt(2)
	v_pk_add_f32 v[16:17], v[16:17], v[64:65]
	v_lshl_add_u64 v[80:81], s[46:47], 0, v[6:7]
	v_ashrrev_i32_e32 v79, 31, v78
	v_pk_add_f32 v[18:19], v[18:19], v[66:67]
	s_waitcnt lgkmcnt(1)
	v_pk_add_f32 v[14:15], v[14:15], v[70:71]
	v_pk_add_f32 v[12:13], v[12:13], v[68:69]
	s_waitcnt lgkmcnt(0)
	v_pk_add_f32 v[16:17], v[16:17], v[72:73]
	v_lshl_add_u64 v[78:79], v[78:79], 1, v[80:81]
	v_pk_add_f32 v[18:19], v[18:19], v[74:75]
	v_add_co_u32_e32 v78, vcc, 0xe1a0000, v78
	v_readlane_b32 s41, v252, 1
	s_nop 0
	v_addc_co_u32_e32 v79, vcc, 0, v79, vcc
	v_readlane_b32 s42, v252, 2
	v_readlane_b32 s43, v252, 3
	v_readlane_b32 s44, v252, 4
	v_readlane_b32 s45, v252, 5
	s_waitcnt vmcnt(0)
	v_pk_mul_f32 v[14:15], v[14:15], v[76:77] op_sel_hi:[1,0]
	v_pk_mul_f32 v[12:13], v[12:13], v[76:77] op_sel_hi:[1,0]
	v_pk_mul_f32 v[16:17], v[16:17], v[76:77] op_sel_hi:[1,0]
	v_pk_mul_f32 v[18:19], v[18:19], v[76:77] op_sel_hi:[1,0]
	v_max_f32_e32 v6, 0, v12
	v_max_f32_e32 v12, 0, v13
	v_max_f32_e32 v13, 0, v14
	v_max_f32_e32 v14, 0, v15
	v_max_f32_e32 v15, 0, v16
	v_max_f32_e32 v16, 0, v17
	v_max_f32_e32 v17, 0, v18
	v_max_f32_e32 v18, 0, v19
	v_mul_f32_e32 v12, v12, v12
	v_mul_f32_e32 v13, v13, v13
	v_mul_f32_e32 v14, v14, v14
	v_mul_f32_e32 v15, v15, v15
	v_mul_f32_e32 v6, v6, v6
	v_mul_f32_e32 v16, v16, v16
	v_mul_f32_e32 v17, v17, v17
	v_mul_f32_e32 v18, v18, v18
	v_cvt_pk_bf16_f32 v12, v6, v12
	v_cvt_pk_bf16_f32 v13, v13, v14
	v_cvt_pk_bf16_f32 v14, v15, v16
	v_cvt_pk_bf16_f32 v15, v17, v18
	global_store_dwordx4 v[78:79], v[12:15], off sc0 sc1
	s_branch .LBB0_1088
.LBB0_1091:
	s_waitcnt vmcnt(0)
	s_barrier
	s_mov_b64 s[0:1], exec
	v_readlane_b32 s6, v252, 9
	v_readlane_b32 s7, v252, 10
	s_and_b64 s[6:7], s[0:1], s[6:7]
	s_mov_b64 exec, s[6:7]
	s_cbranch_execz .LBB0_1143
	v_readlane_b32 s30, v252, 11
	v_readlane_b32 s31, v252, 12
	v_readlane_b32 s32, v252, 48
	v_mov_b32_e32 v5, 1
	v_mov_b32_e32 v22, 0
	s_add_u32 s36, s30, 0x11000
	s_addc_u32 s37, s31, 0
	s_and_b32 s32, s32, 63
	s_lshl_b32 s32, s32, 8
	s_add_u32 s34, s30, 0xc000
	s_addc_u32 s35, s31, 0
	v_mov_b32_e32 v4, s32
	global_atomic_add v22, v5, s[36:37]
	s_cmpk_lg_u32 s86, 0x100
	s_cbranch_scc1 .Lxb6_global
	s_cmp_eq_u32 s99, 0
	s_cbranch_scc1 .Lxb6_nowb
	buffer_wbl2 sc1
	s_waitcnt vmcnt(0)
.Lxb6_nowb:
	global_atomic_add v4, v5, s[34:35]
	s_mov_b32 s42, 0
.Lxb6_gspin:
	global_load_dword v8, v4, s[34:35] sc1
	s_waitcnt vmcnt(0)
	v_cmp_lt_u32_e32 vcc, 3, v8
	s_cbranch_vccnz .Lxb6_acq
	s_add_i32 s42, s42, 1
	s_cmp_lt_u32 s42, 0x400000
	s_cbranch_scc0 .Lxb6_acq
	s_sleep 1
	s_branch .Lxb6_gspin
.Lxb6_acq:
	buffer_inv sc1
	s_waitcnt vmcnt(0)
	s_branch .Lxb6_end
.Lxb6_global:
	v_readlane_b32 s30, v252, 11
	v_readlane_b32 s31, v252, 12
	v_readlane_b32 s32, v252, 13
	v_mov_b32_e32 v5, 1
	v_mov_b32_e32 v22, 0
	s_add_u32 s34, s30, 0x1400
	s_addc_u32 s35, s31, 0
	s_lshl_b32 s32, s32, 8
	s_add_u32 s40, s30, 0x3400
	s_addc_u32 s41, s31, 0
	v_mov_b32_e32 v4, s32
	s_mov_b32 s42, 0
	global_atomic_add v6, v4, v5, s[34:35] sc0
	s_mul_i32 s33, s86, 6
	s_mul_i32 s39, s98, 6
	s_waitcnt vmcnt(0)
	v_readfirstlane_b32 s38, v6
	v_mov_b32_e32 v7, s98
	s_add_i32 s38, s38, 1
	s_cmp_lg_u32 s38, s39
	s_cbranch_scc1 .Lxb6_spin
	buffer_wbl2 sc1
	s_waitcnt vmcnt(0)
	global_atomic_add v22, v7, s[40:41]

.Lxb6_end:
.LBB0_1143:
	s_or_b64 exec, exec, s[0:1]
	v_mov_b32_e32 v148, v176
	s_waitcnt lgkmcnt(0)
	s_barrier
	s_and_b64 vcc, exec, s[4:5]
	v_readfirstlane_b32 s33, v148
	s_cbranch_vccnz .LBB0_1218
	s_ashr_i32 s36, s72, 31
	s_lshr_b32 s0, s36, 29
	s_add_i32 s7, s72, s0
	s_and_b32 s0, s7, -8
	s_sub_i32 s6, s72, s0
	s_cmp_gt_i32 s6, -1
	s_cbranch_scc0 .LBB0_1146
	s_lshl_b32 s2, s6, 5
	s_ashr_i32 s0, s7, 3
	s_cbranch_execz .LBB0_1147
	s_branch .LBB0_1148

.LBB0_1216:
	s_or_b64 exec, exec, s[0:1]
	v_readlane_b32 s14, v252, 11
	v_readlane_b32 s15, v252, 12
	v_mov_b32_e32 v132, 0
	s_mov_b32 s16, 0
	s_add_u32 s14, s14, 0x11000
	s_addc_u32 s15, s15, 0
.Lgd6_spin:
	global_load_dword v133, v132, s[14:15] sc1
	s_waitcnt vmcnt(0)
	v_cmp_le_u32_e32 vcc, s86, v133
	s_cbranch_vccnz .Lgd6_ok
	s_add_i32 s16, s16, 1
	s_cmp_lt_u32 s16, 0x400000
	s_cbranch_scc0 .Lgd6_ok
	s_sleep 1
	s_branch .Lgd6_spin
.Lgd6_ok:
	v_add_f32_e32 v129, 0, v129
	v_add_f32_e32 v129, v129, v134
	v_add_f32_e32 v129, v129, v135
	v_add_f32_e32 v129, v129, v137
	v_mov_b32_e32 v130, 0x358637bd
	v_fmac_f32_e32 v130, 0x3a800000, v129
	s_mov_b32 s0, 0xf800000
	v_mul_f32_e32 v129, 0x4f800000, v130
	v_cmp_gt_f32_e32 vcc, s0, v130
	s_nop 1
	v_cndmask_b32_e32 v129, v130, v129, vcc
	v_sqrt_f32_e32 v130, v129
	s_nop 0
	v_add_u32_e32 v131, -1, v130
	v_fma_f32 v132, -v131, v130, v129
	v_cmp_ge_f32_e64 s[0:1], 0, v132
	v_add_u32_e32 v132, 1, v130
	s_nop 0
	v_cndmask_b32_e64 v131, v130, v131, s[0:1]
	v_fma_f32 v130, -v132, v130, v129
	v_cmp_lt_f32_e64 s[0:1], 0, v130
	s_nop 1
	v_cndmask_b32_e64 v130, v131, v132, s[0:1]
	v_mul_f32_e32 v131, 0x37800000, v130
	v_cndmask_b32_e32 v130, v130, v131, vcc
	v_mov_b32_e32 v131, 0x260
	v_cmp_class_f32_e32 vcc, v129, v131
	s_nop 1
	v_cndmask_b32_e32 v129, v130, v129, vcc
	v_div_scale_f32 v130, s[0:1], v129, v129, 1.0
	v_rcp_f32_e32 v131, v130
	s_nop 0
	v_fma_f32 v132, -v130, v131, 1.0
	v_fmac_f32_e32 v131, v132, v131
	v_div_scale_f32 v132, vcc, 1.0, v129, 1.0
	v_mul_f32_e32 v133, v132, v131
	v_fma_f32 v134, -v130, v133, v132
	v_fmac_f32_e32 v133, v134, v131
	v_fma_f32 v130, -v130, v133, v132
	v_div_fmas_f32 v130, v130, v131, v133
	v_div_fixup_f32 v130, v130, v129, 1.0
	v_mad_u64_u32 v[128:129], s[0:1], v148, -12, v[128:129]
	ds_write_b32 v128, v130 offset:8192
	v_mov_b32_e32 v128, s20

.LBB0_1223:
	v_lshl_add_u64 v[32:33], s[4:5], 0, v[22:23]
	v_add_co_u32_e32 v54, vcc, 0xe1a0000, v32
	v_lshl_add_u64 v[34:35], s[4:5], 0, v[24:25]
	s_nop 0
	v_addc_co_u32_e32 v55, vcc, 0, v33, vcc
	v_add_co_u32_e32 v60, vcc, 0x1920000, v34
	v_lshl_add_u64 v[52:53], s[4:5], 0, v[26:27]
	s_nop 0
	v_addc_co_u32_e32 v61, vcc, 0, v35, vcc
	v_add_co_u32_e32 v62, vcc, 0x1920000, v52
	global_load_dwordx4 v[32:35], v[54:55], off sc1
	global_load_dwordx4 v[36:39], v[54:55], off offset:64 sc1
	global_load_dwordx4 v[40:43], v[54:55], off offset:128 sc1
	global_load_dwordx4 v[44:47], v[54:55], off offset:192 sc1
	global_load_dwordx4 v[48:51], v[60:61], off sc1
	v_addc_co_u32_e32 v63, vcc, 0, v53, vcc
	global_load_dwordx4 v[52:55], v[60:61], off offset:64 sc1
	global_load_dwordx4 v[56:59], v[62:63], off sc1
	s_add_i32 s6, s6, 4
	s_add_u32 s4, s4, 0x100
	s_addc_u32 s5, s5, 0
	s_cmp_lt_u32 s6, 12
	s_waitcnt vmcnt(2)
	v_mfma_f32_16x16x32_bf16 v[0:3], v[48:51], v[32:35], v[0:3]
	global_load_dwordx4 v[48:51], v[62:63], off offset:64 sc1
	s_waitcnt vmcnt(1)
	v_mfma_f32_16x16x32_bf16 v[4:7], v[56:59], v[32:35], v[4:7]
	global_load_dwordx4 v[32:35], v[60:61], off offset:128 sc1
	v_mfma_f32_16x16x32_bf16 v[0:3], v[52:55], v[36:39], v[0:3]
	global_load_dwordx4 v[52:55], v[62:63], off offset:128 sc1
	s_waitcnt vmcnt(2)
	v_mfma_f32_16x16x32_bf16 v[4:7], v[48:51], v[36:39], v[4:7]
	global_load_dwordx4 v[36:39], v[60:61], off offset:192 sc1
	s_waitcnt vmcnt(2)
	v_mfma_f32_16x16x32_bf16 v[0:3], v[32:35], v[40:43], v[0:3]
	global_load_dwordx4 v[32:35], v[62:63], off offset:192 sc1
	s_waitcnt vmcnt(2)
	v_mfma_f32_16x16x32_bf16 v[4:7], v[52:55], v[40:43], v[4:7]
	s_waitcnt vmcnt(1)
	v_mfma_f32_16x16x32_bf16 v[0:3], v[36:39], v[44:47], v[0:3]
	s_waitcnt vmcnt(0)
	v_mfma_f32_16x16x32_bf16 v[4:7], v[32:35], v[44:47], v[4:7]
	s_cbranch_scc1 .LBB0_1223
	v_add_u32_e32 v19, s22, v9
	s_andn2_b64 vcc, exec, s[10:11]
	s_nop 2
	ds_write_b128 v19, v[0:3]
	s_nop 0
	ds_write_b128 v19, v[4:7] offset:1024
	s_waitcnt lgkmcnt(0)
	s_barrier
	s_cbranch_vccnz .LBB0_1221
	v_add_u32_e32 v19, s23, v9
	ds_read_b128 v[0:3], v19 offset:2048
	ds_read_b128 v[4:7], v19
	ds_read_b128 v[22:25], v19 offset:1024
	ds_read_b128 v[32:35], v19 offset:3072
	ds_read_b128 v[36:39], v19 offset:4096
	v_readlane_b32 s36, v252, 0
	s_waitcnt lgkmcnt(3)
	v_pk_add_f32 v[6:7], v[6:7], v[2:3]
	v_pk_add_f32 v[26:27], v[4:5], v[0:1]
	ds_read_b128 v[0:3], v19 offset:5120
	s_waitcnt lgkmcnt(2)
	v_pk_add_f32 v[24:25], v[24:25], v[34:35]
	s_waitcnt lgkmcnt(1)
	v_pk_add_f32 v[34:35], v[6:7], v[38:39]
	ds_read_b128 v[4:7], v19 offset:6144
	v_pk_add_f32 v[32:33], v[22:23], v[32:33]
	v_pk_add_f32 v[26:27], v[26:27], v[36:37]
	s_waitcnt lgkmcnt(1)
	v_pk_add_f32 v[36:37], v[24:25], v[2:3]
	ds_read_b128 v[22:25], v19 offset:7168
	v_pk_add_f32 v[32:33], v[32:33], v[0:1]
	s_waitcnt lgkmcnt(1)
	v_pk_add_f32 v[34:35], v[34:35], v[6:7]
	ds_read_b128 v[0:3], v19 offset:8192
	v_pk_add_f32 v[26:27], v[26:27], v[4:5]
	ds_read_b128 v[4:7], v19 offset:9216
	s_waitcnt lgkmcnt(2)
	v_pk_add_f32 v[36:37], v[36:37], v[24:25]
	v_pk_add_f32 v[32:33], v[32:33], v[22:23]
	ds_read_b128 v[22:25], v19 offset:10240
	s_waitcnt lgkmcnt(2)
	v_pk_add_f32 v[34:35], v[34:35], v[2:3]
	v_pk_add_f32 v[26:27], v[26:27], v[0:1]
	s_waitcnt lgkmcnt(1)
	v_pk_add_f32 v[36:37], v[36:37], v[6:7]
	ds_read_b128 v[0:3], v19 offset:11264
	v_pk_add_f32 v[32:33], v[32:33], v[4:5]
	ds_read_b128 v[4:7], v19 offset:12288
	s_waitcnt lgkmcnt(2)
	v_pk_add_f32 v[24:25], v[34:35], v[24:25]
	v_pk_add_f32 v[26:27], v[26:27], v[22:23]
	s_waitcnt lgkmcnt(1)
	v_pk_add_f32 v[36:37], v[36:37], v[2:3]
	v_pk_add_f32 v[38:39], v[32:33], v[0:1]
	ds_read_b128 v[0:3], v19 offset:13312
	s_waitcnt lgkmcnt(1)
	v_pk_add_f32 v[6:7], v[24:25], v[6:7]
	ds_read_b128 v[22:25], v19 offset:14336
	ds_read_b128 v[32:35], v19 offset:15360
	v_pk_add_f32 v[26:27], v[26:27], v[4:5]
	s_waitcnt lgkmcnt(2)
	v_pk_add_f32 v[2:3], v[36:37], v[2:3]
	v_pk_add_f32 v[36:37], v[38:39], v[0:1]
	s_waitcnt lgkmcnt(1)
	v_pk_add_f32 v[4:5], v[6:7], v[24:25]
	v_pk_add_f32 v[6:7], v[26:27], v[22:23]
	v_mul_f32_e32 v20, v5, v5
	v_mul_f32_e32 v19, v7, v7
	s_waitcnt lgkmcnt(0)
	v_pk_add_f32 v[0:1], v[2:3], v[34:35]
	v_pk_add_f32 v[2:3], v[36:37], v[32:33]
	v_fmac_f32_e32 v19, v6, v6
	v_fmac_f32_e32 v20, v4, v4
	v_add_f32_e32 v19, v19, v20
	v_mul_f32_e32 v20, v3, v3
	v_mul_f32_e32 v22, v1, v1
	v_fmac_f32_e32 v20, v2, v2
	v_fmac_f32_e32 v22, v0, v0
	v_add_f32_e32 v20, v20, v22
	v_and_b32_e32 v22, 64, v177
	v_add_f32_e32 v19, v19, v20
	v_xor_b32_e32 v20, 16, v177
	v_add_u32_e32 v22, 64, v22
	v_cmp_lt_i32_e32 vcc, v20, v22
	s_add_i32 s4, s72, s2
	v_readlane_b32 s40, v252, 4
	v_cndmask_b32_e32 v20, v177, v20, vcc
	v_lshlrev_b32_e32 v26, 2, v20
	ds_bpermute_b32 v20, v26, v19
	v_readlane_b32 s41, v252, 5
	s_and_b32 s6, s4, 7
	v_readlane_b32 s42, v252, 6
	v_readlane_b32 s43, v252, 7
	s_waitcnt lgkmcnt(0)
	v_add_f32_e32 v19, v19, v20
	v_xor_b32_e32 v20, 32, v177
	v_cmp_lt_i32_e32 vcc, v20, v22
	s_mov_b64 s[16:17], s[40:41]
	s_ashr_i32 s4, s4, 3
	v_cndmask_b32_e32 v20, v177, v20, vcc
	v_lshlrev_b32_e32 v27, 2, v20
	s_lshl_b32 s5, s6, 12
	ds_bpermute_b32 v20, v27, v19
	s_mov_b64 s[18:19], s[42:43]
	s_add_u32 s5, s18, s5
	s_addc_u32 s15, s19, 0
	s_add_u32 s14, s5, 0xe4b0000
	s_addc_u32 s15, s15, 0
	v_readlane_b32 s37, v252, 1
	v_readlane_b32 s38, v252, 2
	v_readlane_b32 s39, v252, 3
	s_and_saveexec_b64 s[16:17], s[0:1]
	s_cbranch_execz .LBB0_1227
	s_waitcnt lgkmcnt(0)
	v_add_f32_e32 v20, v19, v20
	v_mov_b32_e32 v19, v11
	v_lshl_add_u64 v[22:23], s[14:15], 0, v[18:19]
	s_ashr_i32 s5, s4, 31
	v_lshl_add_u64 v[22:23], s[4:5], 3, v[22:23]
	global_store_dwordx2 v[22:23], v[20:21], off sc1

	.amdhsa_kernel _Z14fwd_megakernel3Ctx
		.amdhsa_group_segment_fixed_size 0
		.amdhsa_private_segment_fixed_size 0
		.amdhsa_kernarg_size 416
		.amdhsa_user_sgpr_count 2
		.amdhsa_user_sgpr_dispatch_ptr 0
		.amdhsa_user_sgpr_queue_ptr 0
		.amdhsa_user_sgpr_kernarg_segment_ptr 1
		.amdhsa_user_sgpr_dispatch_id 0
		.amdhsa_user_sgpr_kernarg_preload_length 0
		.amdhsa_user_sgpr_kernarg_preload_offset 0
		.amdhsa_user_sgpr_private_segment_size 0
		.amdhsa_uses_dynamic_stack 0
		.amdhsa_enable_private_segment 0
		.amdhsa_system_sgpr_workgroup_id_x 1
		.amdhsa_system_sgpr_workgroup_id_y 0
		.amdhsa_system_sgpr_workgroup_id_z 0
		.amdhsa_system_sgpr_workgroup_info 0
		.amdhsa_system_vgpr_workitem_id 2
		.amdhsa_next_free_vgpr 253
		.amdhsa_next_free_sgpr 101
		.amdhsa_accum_offset 256
		.amdhsa_reserve_vcc 1
		.amdhsa_float_round_mode_32 0
		.amdhsa_float_round_mode_16_64 0
		.amdhsa_float_denorm_mode_32 3
		.amdhsa_float_denorm_mode_16_64 3
		.amdhsa_dx10_clamp 1
		.amdhsa_ieee_mode 1
		.amdhsa_fp16_overflow 0
		.amdhsa_tg_split 0
		.amdhsa_exception_fp_ieee_invalid_op 0
		.amdhsa_exception_fp_denorm_src 0
		.amdhsa_exception_fp_ieee_div_zero 0
		.amdhsa_exception_fp_ieee_overflow 0
		.amdhsa_exception_fp_ieee_underflow 0
		.amdhsa_exception_fp_ieee_inexact 0
		.amdhsa_exception_int_div_zero 0
	.end_amdhsa_kernel

amdhsa.kernels:
  - .agpr_count:     0
    .args:
      - .offset:         0
        .size:           160
        .value_kind:     by_value
      - .offset:         160
        .size:           4
        .value_kind:     hidden_block_count_x
      - .offset:         164
        .size:           4
        .value_kind:     hidden_block_count_y
      - .offset:         168
        .size:           4
        .value_kind:     hidden_block_count_z
      - .offset:         172
        .size:           2
        .value_kind:     hidden_group_size_x
      - .offset:         174
        .size:           2
        .value_kind:     hidden_group_size_y
      - .offset:         176
        .size:           2
        .value_kind:     hidden_group_size_z
      - .offset:         178
        .size:           2
        .value_kind:     hidden_remainder_x
      - .offset:         180
        .size:           2
        .value_kind:     hidden_remainder_y
      - .offset:         182
        .size:           2
        .value_kind:     hidden_remainder_z
      - .offset:         200
        .size:           8
        .value_kind:     hidden_global_offset_x
      - .offset:         208
        .size:           8
        .value_kind:     hidden_global_offset_y
      - .offset:         216
        .size:           8
        .value_kind:     hidden_global_offset_z
      - .offset:         224
        .size:           2
        .value_kind:     hidden_grid_dims
      - .offset:         248
        .size:           8
        .value_kind:     hidden_multigrid_sync_arg
      - .offset:         280
        .size:           4
        .value_kind:     hidden_dynamic_lds_size
    .group_segment_fixed_size: 0
    .kernarg_segment_align: 8
    .kernarg_segment_size: 416
    .language:       OpenCL C
    .language_version:
      - 2
      - 0
    .max_flat_workgroup_size: 512
    .name:           _Z14fwd_megakernel3Ctx
    .private_segment_fixed_size: 0
    .sgpr_count:     107
    .sgpr_spill_count: 59
    .symbol:         _Z14fwd_megakernel3Ctx.kd
    .uniform_work_group_size: 1
    .uses_dynamic_stack: false
    .vgpr_count:     253
    .vgpr_spill_count: 0
    .wavefront_size: 64
